# P0 row loop: second wave of each SIMD starts half a period late (s_sleep) so loads and compute of the two waves alternate
# baseline (speedup 1.0000x reference)
.LBB0_137:
	s_or_b64 exec, exec, s[4:5]
	s_cmpk_gt_i32 s33, 0x3fff
	s_waitcnt lgkmcnt(0)
	s_barrier
	s_cbranch_scc1 .LBB0_142
	v_mbcnt_lo_u32_b32 v105, -1, 0
	v_mbcnt_hi_u32_b32 v105, -1, v105
	v_and_b32_e32 v106, 64, v105
	v_add_u32_e32 v106, 64, v106
	v_xor_b32_e32 v107, 1, v105
	v_cmp_lt_i32_e32 vcc, v107, v106
	v_lshl_add_u32 v124, v167, 5, 0
	ds_read_b128 v[0:3], v124
	ds_read_b128 v[4:7], v124 offset:16
	ds_read_b128 v[8:11], v124 offset:2048
	ds_read_b128 v[12:15], v124 offset:2064
	ds_read_b128 v[16:19], v124 offset:4096
	ds_read_b128 v[20:23], v124 offset:4112
	ds_read_b128 v[24:27], v124 offset:6144
	ds_read_b128 v[28:31], v124 offset:6160
	ds_read_b128 v[32:35], v124 offset:8192
	ds_read_b128 v[36:39], v124 offset:8208
	ds_read_b128 v[40:43], v124 offset:10240
	ds_read_b128 v[44:47], v124 offset:10256
	ds_read_b128 v[48:51], v124 offset:12288
	ds_read_b128 v[52:55], v124 offset:12304
	ds_read_b128 v[56:59], v124 offset:14336
	ds_read_b128 v[60:63], v124 offset:14352
	ds_read_b128 v[64:67], v124 offset:16384
	ds_read_b128 v[68:71], v124 offset:16400
	ds_read_b128 v[72:75], v124 offset:18432
	ds_read_b128 v[76:79], v124 offset:18448
	ds_read_b128 v[80:83], v124 offset:20480
	ds_read_b128 v[84:87], v124 offset:20496
	ds_read_b128 v[88:91], v124 offset:22528
	ds_read_b128 v[92:95], v124 offset:22544
	ds_read_b128 v[96:99], v124 offset:24576
	ds_read_b128 v[100:103], v124 offset:24592
	v_cndmask_b32_e32 v107, v105, v107, vcc
	v_lshlrev_b32_e32 v169, 2, v107
	v_xor_b32_e32 v107, 2, v105
	v_cmp_lt_i32_e32 vcc, v107, v106
	s_lshl_b32 s18, s33, 1
	s_ashr_i32 s19, s18, 31
	v_cndmask_b32_e32 v107, v105, v107, vcc
	v_lshlrev_b32_e32 v170, 2, v107
	v_xor_b32_e32 v107, 4, v105
	v_cmp_lt_i32_e32 vcc, v107, v106
	s_lshl_b64 s[10:11], s[18:19], 5
	s_lshl_b32 s16, s90, 4
	v_cndmask_b32_e32 v107, v105, v107, vcc
	v_lshlrev_b32_e32 v171, 2, v107
	v_xor_b32_e32 v107, 8, v105
	v_cmp_lt_i32_e32 vcc, v107, v106
	s_ashr_i32 s17, s16, 31
	s_lshl_b64 s[20:21], s[16:17], 5
	v_cndmask_b32_e32 v107, v105, v107, vcc
	v_lshlrev_b32_e32 v172, 2, v107
	v_xor_b32_e32 v107, 16, v105
	v_cmp_lt_i32_e32 vcc, v107, v106
	s_lshl_b64 s[24:25], s[16:17], 11
	s_mov_b32 s28, 0x3a800000
	v_cndmask_b32_e32 v107, v105, v107, vcc
	v_lshlrev_b32_e32 v173, 2, v107
	v_xor_b32_e32 v107, 32, v105
	v_cmp_lt_i32_e32 vcc, v107, v106
	v_mov_b32_e32 v166, 0x358637bd
	s_nop 0
	v_cndmask_b32_e32 v105, v105, v107, vcc
	v_lshlrev_b32_e32 v174, 2, v105
	v_and_b32_e32 v105, 16, v104
	v_cmp_eq_u32_e64 s[0:1], 0, v105
	v_and_b32_e32 v105, 8, v104
	v_cmp_eq_u32_e64 s[8:9], 0, v105
	v_and_b32_e32 v105, 4, v104
	v_and_b32_e32 v104, 3, v104
	v_cmp_eq_u32_e64 s[4:5], 0, v105
	v_cmp_eq_u32_e64 s[6:7], 0, v104
	v_and_or_b32 v104, v167, 60, s10
	v_mov_b32_e32 v105, s11
	s_mov_b64 s[10:11], 0x1f200000
	v_lshl_add_u64 v[160:161], v[104:105], 0, s[10:11]
	s_lshl_b64 s[10:11], s[18:19], 11
	v_lshl_or_b32 v162, v167, 4, s10
	v_mov_b32_e32 v163, s11
	s_lshl_b64 s[10:11], s[18:19], 12
	s_add_u32 s10, s56, s10
	v_lshlrev_b32_e32 v104, 5, v167
	v_mov_b32_e32 v105, 0
	s_addc_u32 s11, s57, s11
	v_lshl_add_u64 v[104:105], s[10:11], 0, v[104:105]
	s_mov_b64 s[10:11], 0x1000
	v_lshl_add_u64 v[164:165], v[104:105], 0, s[10:11]
	ds_read_b128 v[104:107], v124 offset:26624
	ds_read_b128 v[108:111], v124 offset:26640
	ds_read_b128 v[112:115], v124 offset:28672
	ds_read_b128 v[116:119], v124 offset:28688
	ds_read_b128 v[120:123], v124 offset:30720
	ds_read_b128 v[124:127], v124 offset:30736
	v_cmp_gt_u32_e32 vcc, 32, v167
	s_lshl_b64 s[26:27], s[16:17], 12
	s_mov_b32 s17, 0x800000
	s_brev_b32 s19, 32
	v_readfirstlane_b32 s100, v204
	s_and_b32 s100, s100, 0x100
	s_cbranch_scc0 .Lp0_nostag
	s_sleep 100
